# plus spatial-gating epilogue: all u/gate loads issued with the first pair
# baseline (speedup 1.0000x reference)
; __device__ __forceinline__ unsigned pk2(float lo, float hi) { unsigned r; asm("v_cvt_pk_bf16_f32 %0, %1, %2" : "=v"(r) : "v"(lo), "v"(hi)); return r; }
; __device__ __forceinline__ void mix_sgu(const bf16* h, const float* lng, const float* lnb, const float* sgw, const float* sgb, bf16* ycat, char* lds, int wg, int nwg) {
;     ...
;         { const int t = 16 * wid + li; const float bias = sgb[grp * 128 + t];
;           const bf16* hr = h + (m0 + t) * NH + 128 * grp + 4 * g; bf16* yr = ycat + (m0 + t) * DM + Y_D + 128 * grp + 4 * g;
; #pragma unroll
;           for (int nb = 0; nb < 8; ++nb) { const v2u uu = *(const v2u*)(hr + C_DU + 16 * nb), gd = *(const v2u*)(hr + C_GD + 16 * nb);
;               v2u o; o.x = pk2(__uint_as_float(uu.x << 16) * (acc[nb][0] + bias) * __uint_as_float(gd.x << 16), __uint_as_float(uu.x & 0xffff0000u) * (acc[nb][1] + bias) * __uint_as_float(gd.x & 0xffff0000u));
;               o.y = pk2(__uint_as_float(uu.y << 16) * (acc[nb][2] + bias) * __uint_as_float(gd.y << 16), __uint_as_float(uu.y & 0xffff0000u) * (acc[nb][3] + bias) * __uint_as_float(gd.y & 0xffff0000u));
;               *(v2u*)(yr + 16 * nb) = o; } }
.LBB0_675:
	v_add_u32_e32 v58, s40, v38
	v_ashrrev_i32_e32 v59, 31, v58
	v_lshl_add_u64 v[58:59], v[58:59], 2, s[2:3]
	global_load_dword v77, v[58:59], off
	v_lshl_add_u64 v[58:59], s[24:25], 0, v[38:39]
	v_mov_b64_e32 v[60:61], s[0:1]
	v_mad_u64_u32 v[60:61], s[24:25], v58, s13, v[60:61]
	v_mov_b32_e32 v62, v61
	v_mad_u64_u32 v[62:63], s[24:25], v59, s13, v[62:63]
	v_lshlrev_b64 v[58:59], 12, v[58:59]
	s_lshl_b32 s28, s40, 1
	v_lshl_add_u64 v[58:59], s[38:39], 0, v[58:59]
	v_mov_b32_e32 v61, v62
	v_mov_b32_e32 v57, v169
	v_lshl_add_u64 v[58:59], v[58:59], 0, s[28:29]
	v_lshl_add_u64 v[60:61], v[60:61], 0, s[28:29]
	v_lshl_add_u64 v[78:79], v[58:59], 0, v[56:57]
	s_mov_b64 s[24:25], 0x12800c00
	v_lshl_add_u64 v[60:61], v[60:61], 0, v[56:57]
	v_lshl_add_u64 v[58:59], v[78:79], 0, s[24:25]
	s_movk_i32 s24, 0x2000
	v_add_co_u32_e32 v62, vcc, s24, v60
	s_movk_i32 s24, 0x3000
	s_nop 0
	v_addc_co_u32_e32 v63, vcc, 0, v61, vcc
	v_add_co_u32_e32 v60, vcc, s24, v60
	global_load_dwordx2 v[80:81], v[62:63], off offset:1024
	s_nop 0
	v_addc_co_u32_e32 v61, vcc, 0, v61, vcc
	global_load_dwordx2 v[82:83], v[60:61], off offset:2048
	global_load_dwordx2 v[84:85], v[62:63], off offset:1056
	global_load_dwordx2 v[100:101], v[60:61], off offset:2080
	global_load_dwordx2 v[86:87], v[62:63], off offset:1088
	global_load_dwordx2 v[102:103], v[60:61], off offset:2112
	global_load_dwordx2 v[88:89], v[62:63], off offset:1120
	global_load_dwordx2 v[104:105], v[60:61], off offset:2144
	global_load_dwordx2 v[90:91], v[62:63], off offset:1152
	global_load_dwordx2 v[106:107], v[60:61], off offset:2176
	global_load_dwordx2 v[92:93], v[62:63], off offset:1184
	global_load_dwordx2 v[108:109], v[60:61], off offset:2208
	global_load_dwordx2 v[94:95], v[62:63], off offset:1216
	global_load_dwordx2 v[110:111], v[60:61], off offset:2240
	global_load_dwordx2 v[96:97], v[62:63], off offset:1248
	global_load_dwordx2 v[112:113], v[60:61], off offset:2272
	s_mov_b32 s24, 0x12800000
	s_add_i32 s26, s26, s86
	s_cmpk_gt_i32 s26, 0xff
	s_waitcnt vmcnt(0)
	v_add_f32_e32 v28, v77, v28
	v_add_f32_e32 v29, v77, v29
	v_add_f32_e32 v30, v77, v30
	v_add_f32_e32 v31, v77, v31
	v_add_f32_e32 v24, v77, v24
	v_add_f32_e32 v25, v77, v25
	v_add_f32_e32 v26, v77, v26
	v_add_f32_e32 v27, v77, v27
	v_add_f32_e32 v20, v77, v20
	v_add_f32_e32 v21, v77, v21
	v_add_f32_e32 v22, v77, v22
	v_add_f32_e32 v23, v77, v23
	v_add_f32_e32 v16, v77, v16
	v_add_f32_e32 v17, v77, v17
	v_add_f32_e32 v18, v77, v18
	v_add_f32_e32 v19, v77, v19
	v_add_f32_e32 v12, v77, v12
	v_add_f32_e32 v13, v77, v13
	v_add_f32_e32 v14, v77, v14
	v_add_f32_e32 v15, v77, v15
	v_add_f32_e32 v8, v77, v8
	v_add_f32_e32 v9, v77, v9
	v_add_f32_e32 v10, v77, v10
	v_add_f32_e32 v11, v77, v11
	v_add_f32_e32 v4, v77, v4
	v_add_f32_e32 v5, v77, v5
	v_add_f32_e32 v6, v77, v6
	s_waitcnt lgkmcnt(0)
; __device__ __forceinline__ unsigned pk2(float lo, float hi) { unsigned r; asm("v_cvt_pk_bf16_f32 %0, %1, %2" : "=v"(r) : "v"(lo), "v"(hi)); return r; }
; __device__ __forceinline__ void mix_sgu(const bf16* h, const float* lng, const float* lnb, const float* sgw, const float* sgb, bf16* ycat, char* lds, int wg, int nwg) {
;     ...
;           for (int nb = 0; nb < 8; ++nb) { const v2u uu = *(const v2u*)(hr + C_DU + 16 * nb), gd = *(const v2u*)(hr + C_GD + 16 * nb);
;               v2u o; o.x = pk2(__uint_as_float(uu.x << 16) * (acc[nb][0] + bias) * __uint_as_float(gd.x << 16), __uint_as_float(uu.x & 0xffff0000u) * (acc[nb][1] + bias) * __uint_as_float(gd.x & 0xffff0000u));
;               o.y = pk2(__uint_as_float(uu.y << 16) * (acc[nb][2] + bias) * __uint_as_float(gd.y << 16), __uint_as_float(uu.y & 0xffff0000u) * (acc[nb][3] + bias) * __uint_as_float(gd.y & 0xffff0000u));
;               *(v2u*)(yr + 16 * nb) = o; } }
	v_lshlrev_b32_e32 v57, 16, v80
	v_mul_f32_e32 v28, v28, v57
	v_add_f32_e32 v7, v77, v7
	v_lshlrev_b32_e32 v57, 16, v82
	v_mul_f32_e32 v28, v28, v57
	v_and_b32_e32 v57, 0xffff0000, v80
	v_mul_f32_e32 v29, v29, v57
	v_and_b32_e32 v57, 0xffff0000, v82
	v_mul_f32_e32 v29, v29, v57
	v_cvt_pk_bf16_f32 v28, v28, v29
	v_lshlrev_b32_e32 v29, 16, v81
	v_mul_f32_e32 v29, v30, v29
	v_lshlrev_b32_e32 v30, 16, v83
	v_mul_f32_e32 v29, v29, v30
	v_and_b32_e32 v30, 0xffff0000, v81
	v_mul_f32_e32 v30, v31, v30
	v_and_b32_e32 v31, 0xffff0000, v83
	v_mul_f32_e32 v30, v30, v31
	v_cvt_pk_bf16_f32 v29, v29, v30
	v_add_co_u32_e32 v30, vcc, s24, v78
	v_add_f32_e32 v0, v77, v0
	s_nop 0
	v_addc_co_u32_e32 v31, vcc, 0, v79, vcc
	global_store_dwordx2 v[30:31], v[28:29], off offset:3072
	s_nop 0
	v_add_f32_e32 v1, v77, v1
	v_add_f32_e32 v2, v77, v2
	v_add_f32_e32 v3, v77, v3
	v_lshlrev_b32_e32 v57, 16, v84
	v_and_b32_e32 v84, 0xffff0000, v84
	v_mul_f32_e32 v24, v24, v57
	v_lshlrev_b32_e32 v57, 16, v100
	v_mul_f32_e32 v25, v25, v84
	v_and_b32_e32 v84, 0xffff0000, v100
	v_mul_f32_e32 v24, v24, v57
	v_mul_f32_e32 v25, v25, v84
	v_cvt_pk_bf16_f32 v24, v24, v25
	v_lshlrev_b32_e32 v25, 16, v85
	v_mul_f32_e32 v25, v26, v25
	v_lshlrev_b32_e32 v26, 16, v101
	v_mul_f32_e32 v25, v25, v26
	v_and_b32_e32 v26, 0xffff0000, v85
	v_mul_f32_e32 v26, v27, v26
	v_and_b32_e32 v27, 0xffff0000, v101
	v_mul_f32_e32 v26, v26, v27
	v_cvt_pk_bf16_f32 v25, v25, v26
	global_store_dwordx2 v[58:59], v[24:25], off offset:32
	s_nop 0
	v_lshlrev_b32_e32 v28, 16, v86
	v_and_b32_e32 v86, 0xffff0000, v86
	v_mul_f32_e32 v20, v20, v28
	v_lshlrev_b32_e32 v28, 16, v102
	v_mul_f32_e32 v21, v21, v86
	v_and_b32_e32 v86, 0xffff0000, v102
	v_mul_f32_e32 v20, v20, v28
	v_mul_f32_e32 v21, v21, v86
	v_cvt_pk_bf16_f32 v20, v20, v21
	v_lshlrev_b32_e32 v21, 16, v87
	v_mul_f32_e32 v21, v22, v21
	v_lshlrev_b32_e32 v22, 16, v103
	v_mul_f32_e32 v21, v21, v22
	v_and_b32_e32 v22, 0xffff0000, v87
	v_mul_f32_e32 v22, v23, v22
	v_and_b32_e32 v23, 0xffff0000, v103
	v_mul_f32_e32 v22, v22, v23
	v_cvt_pk_bf16_f32 v21, v21, v22
	global_store_dwordx2 v[58:59], v[20:21], off offset:64
	s_nop 0
	v_lshlrev_b32_e32 v24, 16, v88
	v_and_b32_e32 v88, 0xffff0000, v88
	v_mul_f32_e32 v16, v16, v24
	v_lshlrev_b32_e32 v24, 16, v104
	v_mul_f32_e32 v17, v17, v88
	v_and_b32_e32 v88, 0xffff0000, v104
	v_mul_f32_e32 v16, v16, v24
	v_mul_f32_e32 v17, v17, v88
	v_cvt_pk_bf16_f32 v16, v16, v17
	v_lshlrev_b32_e32 v17, 16, v89
	v_mul_f32_e32 v17, v18, v17
	v_lshlrev_b32_e32 v18, 16, v105
	v_mul_f32_e32 v17, v17, v18
	v_and_b32_e32 v18, 0xffff0000, v89
	v_mul_f32_e32 v18, v19, v18
	v_and_b32_e32 v19, 0xffff0000, v105
	v_mul_f32_e32 v18, v18, v19
	v_cvt_pk_bf16_f32 v17, v17, v18
	global_store_dwordx2 v[58:59], v[16:17], off offset:96
	s_nop 0
	v_lshlrev_b32_e32 v20, 16, v90
	v_and_b32_e32 v90, 0xffff0000, v90
	v_mul_f32_e32 v12, v12, v20
	v_lshlrev_b32_e32 v20, 16, v106
	v_mul_f32_e32 v13, v13, v90
	v_and_b32_e32 v90, 0xffff0000, v106
	v_mul_f32_e32 v12, v12, v20
	v_mul_f32_e32 v13, v13, v90
	v_cvt_pk_bf16_f32 v12, v12, v13
	v_lshlrev_b32_e32 v13, 16, v91
	v_mul_f32_e32 v13, v14, v13
	v_lshlrev_b32_e32 v14, 16, v107
	v_mul_f32_e32 v13, v13, v14
	v_and_b32_e32 v14, 0xffff0000, v91
	v_mul_f32_e32 v14, v15, v14
	v_and_b32_e32 v15, 0xffff0000, v107
	v_mul_f32_e32 v14, v14, v15
	v_cvt_pk_bf16_f32 v13, v13, v14
	global_store_dwordx2 v[58:59], v[12:13], off offset:128
	s_nop 0
	v_lshlrev_b32_e32 v16, 16, v92
	v_and_b32_e32 v92, 0xffff0000, v92
	v_mul_f32_e32 v8, v8, v16
	v_lshlrev_b32_e32 v16, 16, v108
	v_mul_f32_e32 v9, v9, v92
	v_and_b32_e32 v92, 0xffff0000, v108
	v_mul_f32_e32 v8, v8, v16
	v_mul_f32_e32 v9, v9, v92
	v_cvt_pk_bf16_f32 v8, v8, v9
	v_lshlrev_b32_e32 v9, 16, v93
	v_mul_f32_e32 v9, v10, v9
	v_lshlrev_b32_e32 v10, 16, v109
	v_mul_f32_e32 v9, v9, v10
	v_and_b32_e32 v10, 0xffff0000, v93
	v_mul_f32_e32 v10, v11, v10
	v_and_b32_e32 v11, 0xffff0000, v109
	v_mul_f32_e32 v10, v10, v11
	v_cvt_pk_bf16_f32 v9, v9, v10
	global_store_dwordx2 v[58:59], v[8:9], off offset:160
	s_nop 0
	v_lshlrev_b32_e32 v12, 16, v94
	v_and_b32_e32 v94, 0xffff0000, v94
	v_mul_f32_e32 v4, v4, v12
	v_lshlrev_b32_e32 v12, 16, v110
	v_mul_f32_e32 v5, v5, v94
	v_and_b32_e32 v94, 0xffff0000, v110
	v_mul_f32_e32 v4, v4, v12
	v_mul_f32_e32 v5, v5, v94
	v_cvt_pk_bf16_f32 v4, v4, v5
	v_lshlrev_b32_e32 v5, 16, v95
	v_mul_f32_e32 v5, v6, v5
	v_lshlrev_b32_e32 v6, 16, v111
	v_mul_f32_e32 v5, v5, v6
	v_and_b32_e32 v6, 0xffff0000, v95
	v_mul_f32_e32 v6, v7, v6
	v_and_b32_e32 v7, 0xffff0000, v111
	v_mul_f32_e32 v6, v6, v7
	v_cvt_pk_bf16_f32 v5, v5, v6
	global_store_dwordx2 v[58:59], v[4:5], off offset:192
	s_nop 0
	v_lshlrev_b32_e32 v8, 16, v96
	v_and_b32_e32 v96, 0xffff0000, v96
	v_mul_f32_e32 v0, v0, v8
	v_lshlrev_b32_e32 v8, 16, v112
	v_mul_f32_e32 v1, v1, v96
	v_and_b32_e32 v96, 0xffff0000, v112
	v_mul_f32_e32 v0, v0, v8
	v_mul_f32_e32 v1, v1, v96
	v_cvt_pk_bf16_f32 v0, v0, v1
	v_lshlrev_b32_e32 v1, 16, v97
	v_mul_f32_e32 v1, v2, v1
	v_lshlrev_b32_e32 v2, 16, v113
	v_mul_f32_e32 v1, v1, v2
	v_and_b32_e32 v2, 0xffff0000, v97
	v_mul_f32_e32 v2, v3, v2
	v_and_b32_e32 v3, 0xffff0000, v113
	v_mul_f32_e32 v2, v2, v3
	v_cvt_pk_bf16_f32 v1, v1, v2
	global_store_dwordx2 v[58:59], v[0:1], off offset:224
	s_waitcnt lgkmcnt(0)
	s_barrier
	s_cbranch_scc1 .LBB0_679
